# down-projection K-loop: 6 of 10 m0-hazard s_nops per iteration replaced by existing SALU (same transformation as the other three loops)
# speedup vs baseline: 1.0017x; 1.0017x over previous
.LBB0_728:
	s_add_u32 s42, s22, 0x100
	s_addc_u32 s43, s23, 0
	s_add_i32 s50, 0, 0x10000
	s_cmpk_eq_i32 s25, 0x54
	s_cselect_b32 s49, s21, s43
	s_cselect_b32 s48, s20, s42
	s_cselect_b32 s47, s45, s19
	s_cselect_b32 s46, s44, s18
	ds_read_b128 v[42:45], v236
	ds_read_b128 v[46:49], v236 offset:1024
	ds_read_b128 v[50:53], v236 offset:2048
	ds_read_b128 v[54:57], v236 offset:3072
	ds_read_b128 v[154:157], v237
	ds_read_b128 v[168:171], v237 offset:1024
	ds_read_b128 v[172:175], v237 offset:2048
	ds_read_b128 v[180:183], v237 offset:3072
	s_add_i32 m0, s33, 0xc000
	ds_read_b128 v[184:187], v178
	ds_read_b128 v[188:191], v178 offset:1024
	ds_read_b128 v[192:195], v178 offset:2048
	ds_read_b128 v[196:199], v178 offset:3072
	ds_read_b128 v[200:203], v178 offset:4096
	ds_read_b128 v[210:213], v178 offset:5120
	ds_read_b128 v[214:217], v178 offset:6144
	ds_read_b128 v[218:221], v178 offset:7168
	global_load_lds_dwordx4 v164, s[22:23]
	s_add_i32 m0, s33, 0xe000
	s_add_i32 s51, 0, 0x14000
	global_load_lds_dwordx4 v166, s[22:23]
	s_waitcnt vmcnt(8) lgkmcnt(0)
	s_barrier
	v_mfma_f32_16x16x32_bf16 v[142:145], v[42:45], v[184:187], v[142:145]
	v_mfma_f32_16x16x32_bf16 v[138:141], v[50:53], v[184:187], v[138:141]
	v_mfma_f32_16x16x32_bf16 v[126:129], v[42:45], v[192:195], v[126:129]
	v_mfma_f32_16x16x32_bf16 v[122:125], v[50:53], v[192:195], v[122:125]
	v_mfma_f32_16x16x32_bf16 v[110:113], v[42:45], v[200:203], v[110:113]
	v_mfma_f32_16x16x32_bf16 v[106:109], v[50:53], v[200:203], v[106:109]
	v_mfma_f32_16x16x32_bf16 v[94:97], v[42:45], v[214:217], v[94:97]
	v_mfma_f32_16x16x32_bf16 v[90:93], v[50:53], v[214:217], v[90:93]
	v_mfma_f32_16x16x32_bf16 v[142:145], v[46:49], v[188:191], v[142:145]
	v_mfma_f32_16x16x32_bf16 v[138:141], v[54:57], v[188:191], v[138:141]
	v_mfma_f32_16x16x32_bf16 v[126:129], v[46:49], v[196:199], v[126:129]
	v_mfma_f32_16x16x32_bf16 v[122:125], v[54:57], v[196:199], v[122:125]
	v_mfma_f32_16x16x32_bf16 v[110:113], v[46:49], v[210:213], v[110:113]
	v_mfma_f32_16x16x32_bf16 v[106:109], v[54:57], v[210:213], v[106:109]
	v_mfma_f32_16x16x32_bf16 v[94:97], v[46:49], v[218:221], v[94:97]
	v_mfma_f32_16x16x32_bf16 v[90:93], v[54:57], v[218:221], v[90:93]
	v_mfma_f32_16x16x32_bf16 v[134:137], v[154:157], v[184:187], v[134:137]
	v_mfma_f32_16x16x32_bf16 v[130:133], v[172:175], v[184:187], v[130:133]
	v_mfma_f32_16x16x32_bf16 v[118:121], v[154:157], v[192:195], v[118:121]
	v_mfma_f32_16x16x32_bf16 v[114:117], v[172:175], v[192:195], v[114:117]
	v_mfma_f32_16x16x32_bf16 v[102:105], v[154:157], v[200:203], v[102:105]
	v_mfma_f32_16x16x32_bf16 v[98:101], v[172:175], v[200:203], v[98:101]
	v_mfma_f32_16x16x32_bf16 v[86:89], v[154:157], v[214:217], v[86:89]
	v_mfma_f32_16x16x32_bf16 v[82:85], v[172:175], v[214:217], v[82:85]
	v_mfma_f32_16x16x32_bf16 v[134:137], v[168:171], v[188:191], v[134:137]
	v_mfma_f32_16x16x32_bf16 v[130:133], v[180:183], v[188:191], v[130:133]
	v_mfma_f32_16x16x32_bf16 v[118:121], v[168:171], v[196:199], v[118:121]
	v_mfma_f32_16x16x32_bf16 v[114:117], v[180:183], v[196:199], v[114:117]
	v_mfma_f32_16x16x32_bf16 v[102:105], v[168:171], v[210:213], v[102:105]
	v_mfma_f32_16x16x32_bf16 v[98:101], v[180:183], v[210:213], v[98:101]
	v_mfma_f32_16x16x32_bf16 v[86:89], v[168:171], v[218:221], v[86:89]
	v_mfma_f32_16x16x32_bf16 v[82:85], v[180:183], v[218:221], v[82:85]
	s_barrier
	s_add_i32 s22, s50, s16
	s_mov_b32 m0, s22
	ds_read_b128 v[184:187], v178 offset:16384
	ds_read_b128 v[188:191], v178 offset:17408
	ds_read_b128 v[192:195], v178 offset:18432
	ds_read_b128 v[196:199], v178 offset:19456
	ds_read_b128 v[200:203], v178 offset:20480
	ds_read_b128 v[210:213], v178 offset:21504
	ds_read_b128 v[214:217], v178 offset:22528
	ds_read_b128 v[218:221], v178 offset:23552
	global_load_lds_dwordx4 v0, s[46:47]
	s_add_i32 m0, s22, 0x2000
	s_add_i32 s50, s51, s16
	global_load_lds_dwordx4 v158, s[46:47]
	s_mov_b32 m0, s50
	s_add_u32 s22, s46, 0x160000
	s_addc_u32 s23, s47, 0
	global_load_lds_dwordx4 v0, s[22:23]
	s_add_i32 m0, s50, 0x2000
	s_add_u32 s100, s48, 0x80
	global_load_lds_dwordx4 v158, s[22:23]
	s_addc_u32 s101, s49, 0
	s_mov_b32 m0, s33
	s_add_u32 s98, s46, 0x80
	global_load_lds_dwordx4 v162, s[48:49]
	s_mov_b32 m0, s37
	s_addc_u32 s99, s47, 0
	global_load_lds_dwordx4 v160, s[48:49]
	s_waitcnt vmcnt(8) lgkmcnt(0)
	s_barrier
	v_mfma_f32_16x16x32_bf16 v[78:81], v[42:45], v[184:187], v[78:81]
	v_mfma_f32_16x16x32_bf16 v[74:77], v[50:53], v[184:187], v[74:77]
	v_mfma_f32_16x16x32_bf16 v[62:65], v[42:45], v[192:195], v[62:65]
	v_mfma_f32_16x16x32_bf16 v[58:61], v[50:53], v[192:195], v[58:61]
	v_mfma_f32_16x16x32_bf16 v[30:33], v[42:45], v[200:203], v[30:33]
	v_mfma_f32_16x16x32_bf16 v[26:29], v[50:53], v[200:203], v[26:29]
	v_mfma_f32_16x16x32_bf16 v[14:17], v[42:45], v[214:217], v[14:17]
	v_mfma_f32_16x16x32_bf16 v[10:13], v[50:53], v[214:217], v[10:13]
	v_mfma_f32_16x16x32_bf16 v[78:81], v[46:49], v[188:191], v[78:81]
	v_mfma_f32_16x16x32_bf16 v[74:77], v[54:57], v[188:191], v[74:77]
	v_mfma_f32_16x16x32_bf16 v[62:65], v[46:49], v[196:199], v[62:65]
	v_mfma_f32_16x16x32_bf16 v[58:61], v[54:57], v[196:199], v[58:61]
	v_mfma_f32_16x16x32_bf16 v[30:33], v[46:49], v[210:213], v[30:33]
	v_mfma_f32_16x16x32_bf16 v[26:29], v[54:57], v[210:213], v[26:29]
	v_mfma_f32_16x16x32_bf16 v[14:17], v[46:49], v[218:221], v[14:17]
	v_mfma_f32_16x16x32_bf16 v[10:13], v[54:57], v[218:221], v[10:13]
	v_mfma_f32_16x16x32_bf16 v[38:41], v[154:157], v[192:195], v[38:41]
	v_mfma_f32_16x16x32_bf16 v[34:37], v[172:175], v[192:195], v[34:37]
	v_mfma_f32_16x16x32_bf16 v[22:25], v[154:157], v[200:203], v[22:25]
	v_mfma_f32_16x16x32_bf16 v[18:21], v[172:175], v[200:203], v[18:21]
	v_mfma_f32_16x16x32_bf16 v[6:9], v[154:157], v[214:217], v[6:9]
	v_mfma_f32_16x16x32_bf16 v[2:5], v[172:175], v[214:217], v[2:5]
	v_mfma_f32_16x16x32_bf16 v[42:45], v[154:157], v[184:187], v[70:73]
	v_mfma_f32_16x16x32_bf16 v[46:49], v[172:175], v[184:187], v[66:69]
	v_mfma_f32_16x16x32_bf16 v[38:41], v[168:171], v[196:199], v[38:41]
	v_mfma_f32_16x16x32_bf16 v[34:37], v[180:183], v[196:199], v[34:37]
	v_mfma_f32_16x16x32_bf16 v[22:25], v[168:171], v[210:213], v[22:25]
	v_mfma_f32_16x16x32_bf16 v[18:21], v[180:183], v[210:213], v[18:21]
	v_mfma_f32_16x16x32_bf16 v[6:9], v[168:171], v[218:221], v[6:9]
	v_mfma_f32_16x16x32_bf16 v[2:5], v[180:183], v[218:221], v[2:5]
	v_mfma_f32_16x16x32_bf16 v[42:45], v[168:171], v[188:191], v[42:45]
	v_mfma_f32_16x16x32_bf16 v[46:49], v[180:183], v[188:191], v[46:49]
	s_barrier
	s_add_i32 s50, 0, 0x18000
	ds_read_b128 v[50:53], v238
	ds_read_b128 v[54:57], v238 offset:1024
	ds_read_b128 v[66:69], v238 offset:2048
	ds_read_b128 v[70:73], v238 offset:3072
	ds_read_b128 v[154:157], v239
	ds_read_b128 v[168:171], v239 offset:1024
	ds_read_b128 v[172:175], v239 offset:2048
	ds_read_b128 v[180:183], v239 offset:3072
	s_add_u32 s22, s48, 0x160000
	s_addc_u32 s23, s49, 0
	s_mov_b32 m0, s52
	ds_read_b128 v[184:187], v178 offset:32768
	ds_read_b128 v[188:191], v178 offset:33792
	ds_read_b128 v[192:195], v178 offset:34816
	ds_read_b128 v[196:199], v178 offset:35840
	ds_read_b128 v[200:203], v178 offset:36864
	ds_read_b128 v[210:213], v178 offset:37888
	ds_read_b128 v[214:217], v178 offset:38912
	ds_read_b128 v[218:221], v178 offset:39936
	global_load_lds_dwordx4 v162, s[22:23]
	s_mov_b32 m0, s53
	s_add_i32 s51, 0, 0x1c000
	global_load_lds_dwordx4 v160, s[22:23]
	s_waitcnt vmcnt(8) lgkmcnt(0)
	s_barrier
	v_mfma_f32_16x16x32_bf16 v[142:145], v[50:53], v[184:187], v[142:145]
	v_mfma_f32_16x16x32_bf16 v[138:141], v[66:69], v[184:187], v[138:141]
	v_mfma_f32_16x16x32_bf16 v[126:129], v[50:53], v[192:195], v[126:129]
	v_mfma_f32_16x16x32_bf16 v[122:125], v[66:69], v[192:195], v[122:125]
	v_mfma_f32_16x16x32_bf16 v[110:113], v[50:53], v[200:203], v[110:113]
	v_mfma_f32_16x16x32_bf16 v[106:109], v[66:69], v[200:203], v[106:109]
	v_mfma_f32_16x16x32_bf16 v[94:97], v[50:53], v[214:217], v[94:97]
	v_mfma_f32_16x16x32_bf16 v[90:93], v[66:69], v[214:217], v[90:93]
	v_mfma_f32_16x16x32_bf16 v[142:145], v[54:57], v[188:191], v[142:145]
	v_mfma_f32_16x16x32_bf16 v[138:141], v[70:73], v[188:191], v[138:141]
	v_mfma_f32_16x16x32_bf16 v[126:129], v[54:57], v[196:199], v[126:129]
	v_mfma_f32_16x16x32_bf16 v[122:125], v[70:73], v[196:199], v[122:125]
	v_mfma_f32_16x16x32_bf16 v[110:113], v[54:57], v[210:213], v[110:113]
	v_mfma_f32_16x16x32_bf16 v[106:109], v[70:73], v[210:213], v[106:109]
	v_mfma_f32_16x16x32_bf16 v[94:97], v[54:57], v[218:221], v[94:97]
	v_mfma_f32_16x16x32_bf16 v[90:93], v[70:73], v[218:221], v[90:93]
	v_mfma_f32_16x16x32_bf16 v[134:137], v[154:157], v[184:187], v[134:137]
	v_mfma_f32_16x16x32_bf16 v[130:133], v[172:175], v[184:187], v[130:133]
	v_mfma_f32_16x16x32_bf16 v[118:121], v[154:157], v[192:195], v[118:121]
	v_mfma_f32_16x16x32_bf16 v[114:117], v[172:175], v[192:195], v[114:117]
	v_mfma_f32_16x16x32_bf16 v[102:105], v[154:157], v[200:203], v[102:105]
	v_mfma_f32_16x16x32_bf16 v[98:101], v[172:175], v[200:203], v[98:101]
	v_mfma_f32_16x16x32_bf16 v[86:89], v[154:157], v[214:217], v[86:89]
	v_mfma_f32_16x16x32_bf16 v[82:85], v[172:175], v[214:217], v[82:85]
	v_mfma_f32_16x16x32_bf16 v[134:137], v[168:171], v[188:191], v[134:137]
	v_mfma_f32_16x16x32_bf16 v[130:133], v[180:183], v[188:191], v[130:133]
	v_mfma_f32_16x16x32_bf16 v[118:121], v[168:171], v[196:199], v[118:121]
	v_mfma_f32_16x16x32_bf16 v[114:117], v[180:183], v[196:199], v[114:117]
	v_mfma_f32_16x16x32_bf16 v[102:105], v[168:171], v[210:213], v[102:105]
	v_mfma_f32_16x16x32_bf16 v[98:101], v[180:183], v[210:213], v[98:101]
	v_mfma_f32_16x16x32_bf16 v[86:89], v[168:171], v[218:221], v[86:89]
	v_mfma_f32_16x16x32_bf16 v[82:85], v[180:183], v[218:221], v[82:85]
	s_barrier
	s_add_i32 s22, s50, s16
	s_mov_b32 m0, s22
	ds_read_b128 v[184:187], v178 offset:49152
	ds_read_b128 v[188:191], v178 offset:50176
	ds_read_b128 v[192:195], v178 offset:51200
	ds_read_b128 v[196:199], v178 offset:52224
	ds_read_b128 v[200:203], v178 offset:53248
	ds_read_b128 v[210:213], v178 offset:54272
	ds_read_b128 v[214:217], v178 offset:55296
	ds_read_b128 v[218:221], v178 offset:56320
	global_load_lds_dwordx4 v0, s[98:99]
	s_add_i32 m0, s22, 0x2000
	s_add_u32 s22, s46, 0x160080
	s_addc_u32 s23, s47, 0
	s_add_i32 s46, s51, s16
	global_load_lds_dwordx4 v158, s[98:99]
	s_mov_b32 m0, s46
	s_nop 0
	global_load_lds_dwordx4 v0, s[22:23]
	s_add_i32 m0, s46, 0x2000
	s_nop 0
	global_load_lds_dwordx4 v158, s[22:23]
	s_mov_b32 m0, s55
	s_nop 0
	global_load_lds_dwordx4 v162, s[100:101]
	s_mov_b32 m0, s56
	s_nop 0
	global_load_lds_dwordx4 v160, s[100:101]
	s_waitcnt vmcnt(8) lgkmcnt(0)
	s_barrier
	v_mfma_f32_16x16x32_bf16 v[78:81], v[50:53], v[184:187], v[78:81]
	v_mfma_f32_16x16x32_bf16 v[74:77], v[66:69], v[184:187], v[74:77]
	v_mfma_f32_16x16x32_bf16 v[62:65], v[50:53], v[192:195], v[62:65]
	v_mfma_f32_16x16x32_bf16 v[58:61], v[66:69], v[192:195], v[58:61]
	v_mfma_f32_16x16x32_bf16 v[30:33], v[50:53], v[200:203], v[30:33]
	v_mfma_f32_16x16x32_bf16 v[26:29], v[66:69], v[200:203], v[26:29]
	v_mfma_f32_16x16x32_bf16 v[14:17], v[50:53], v[214:217], v[14:17]
	v_mfma_f32_16x16x32_bf16 v[10:13], v[66:69], v[214:217], v[10:13]
	v_mfma_f32_16x16x32_bf16 v[78:81], v[54:57], v[188:191], v[78:81]
	v_mfma_f32_16x16x32_bf16 v[74:77], v[70:73], v[188:191], v[74:77]
	v_mfma_f32_16x16x32_bf16 v[62:65], v[54:57], v[196:199], v[62:65]
	v_mfma_f32_16x16x32_bf16 v[58:61], v[70:73], v[196:199], v[58:61]
	v_mfma_f32_16x16x32_bf16 v[30:33], v[54:57], v[210:213], v[30:33]
	v_mfma_f32_16x16x32_bf16 v[26:29], v[70:73], v[210:213], v[26:29]
	v_mfma_f32_16x16x32_bf16 v[14:17], v[54:57], v[218:221], v[14:17]
	v_mfma_f32_16x16x32_bf16 v[10:13], v[70:73], v[218:221], v[10:13]
	v_mfma_f32_16x16x32_bf16 v[42:45], v[154:157], v[184:187], v[42:45]
	v_mfma_f32_16x16x32_bf16 v[70:73], v[168:171], v[188:191], v[42:45]
	v_mfma_f32_16x16x32_bf16 v[42:45], v[172:175], v[184:187], v[46:49]
	v_mfma_f32_16x16x32_bf16 v[38:41], v[154:157], v[192:195], v[38:41]
	v_mfma_f32_16x16x32_bf16 v[34:37], v[172:175], v[192:195], v[34:37]
	v_mfma_f32_16x16x32_bf16 v[22:25], v[154:157], v[200:203], v[22:25]
	v_mfma_f32_16x16x32_bf16 v[18:21], v[172:175], v[200:203], v[18:21]
	v_mfma_f32_16x16x32_bf16 v[6:9], v[154:157], v[214:217], v[6:9]
	v_mfma_f32_16x16x32_bf16 v[2:5], v[172:175], v[214:217], v[2:5]
	v_mfma_f32_16x16x32_bf16 v[66:69], v[180:183], v[188:191], v[42:45]
	v_mfma_f32_16x16x32_bf16 v[38:41], v[168:171], v[196:199], v[38:41]
	v_mfma_f32_16x16x32_bf16 v[34:37], v[180:183], v[196:199], v[34:37]
	v_mfma_f32_16x16x32_bf16 v[22:25], v[168:171], v[210:213], v[22:25]
	v_mfma_f32_16x16x32_bf16 v[18:21], v[180:183], v[210:213], v[18:21]
	v_mfma_f32_16x16x32_bf16 v[6:9], v[168:171], v[218:221], v[6:9]
	v_mfma_f32_16x16x32_bf16 v[2:5], v[180:183], v[218:221], v[2:5]
	s_barrier
	s_add_i32 s25, s25, 2
	s_add_u32 s18, s18, 0x100
	s_addc_u32 s19, s19, 0
	s_cmpk_gt_u32 s25, 0x55
	s_mov_b64 s[22:23], s[42:43]
	s_cbranch_scc0 .LBB0_728
	s_setprio 0
	s_and_b64 vcc, exec, s[12:13]
	s_cbranch_vccz .LBB0_731
	s_barrier
